# v29 + second half of the weight conversion done by the idle workgroups during layer-0 up-projection round 9
# speedup vs baseline: 1.0058x; 1.0058x over previous
.LBB0_9:
	s_lshr_b32 s87, s2, 6
	s_load_dwordx2 s[2:3], s[0:1], 0x48
	v_and_b32_e32 v21, 31, v0
	v_bfe_u32 v31, v0, 5, 1
	v_lshlrev_b32_e32 v2, 2, v21
	v_mul_u32_u24_e32 v3, 0x84, v31
	s_waitcnt lgkmcnt(0)
	v_writelane_b32 v254, s2, 8
	v_bfe_u32 v29, v0, 3, 3
	s_lshl_b32 s43, s38, 3
	v_writelane_b32 v254, s3, 9
	s_lshl_b32 s2, s87, 14
	s_add_i32 s3, s2, 0
	v_readlane_b32 s4, v254, 2
	v_add3_u32 v28, s3, v2, v3
	v_lshlrev_b32_e32 v2, 3, v0
	s_lshl_b32 s2, s4, 3
	v_and_b32_e32 v2, 56, v2
	v_readlane_b32 s5, v254, 3
	v_writelane_b32 v254, s2, 10
	s_add_i32 s2, s2, s87
	v_mul_u32_u24_e32 v4, 0x84, v2
	v_lshlrev_b32_e32 v5, 2, v29
	s_movk_i32 s100, 0x1fff
	s_mov_b32 s101, 0
	s_mov_b32 s7, 0
	s_cmp_gt_i32 s2, s100
	v_mov_b32_e32 v3, 0
	v_add3_u32 v30, s3, v4, v5
	v_lshlrev_b32_e32 v18, 1, v2
	s_cbranch_scc1 .LBB0_160
.Lcv_loop_entry:
	s_mov_b64 s[12:13], s[88:89]
	s_mov_b64 s[14:15], s[90:91]
	v_mov_b32_e32 v4, v18
	v_mov_b32_e32 v5, v3
	v_lshl_add_u64 v[12:13], s[14:15], 0, v[4:5]
	s_mov_b64 s[4:5], 0x1000000
	s_add_u32 s3, s14, 0x3200000
	v_lshl_add_u64 v[6:7], v[12:13], 0, s[4:5]
	s_mov_b64 s[4:5], 0x980000
	s_addc_u32 s10, s15, 0
	v_lshl_add_u64 v[8:9], v[12:13], 0, s[4:5]
	s_mov_b64 s[4:5], 0x780000
	s_add_u32 s11, s14, 0x1200000
	v_lshl_add_u64 v[10:11], v[12:13], 0, s[4:5]
	s_mov_b64 s[4:5], 0x200000
	v_or_b32_e32 v16, 8, v29
	v_or_b32_e32 v17, 16, v29
	v_or_b32_e32 v20, 24, v29
	s_addc_u32 s12, s15, 0
	v_lshl_add_u64 v[12:13], v[12:13], 0, s[4:5]
	s_lshl_b32 s13, s2, 5
	s_lshl_b32 s14, s43, 5
	s_lshl_b32 s15, s2, 1
	s_lshl_b32 s16, s43, 1
	s_lshl_b32 s17, s2, 4
	s_lshl_b32 s18, s43, 4
	s_lshl_b32 s19, s2, 10
	s_lshl_b32 s20, s43, 10
	s_mov_b32 s21, 0xe000
	s_mov_b32 s22, 0x10000
	s_mov_b32 s23, 0x12000
	s_mov_b32 s24, 0x14000
	s_mov_b32 s25, 0x16000
	s_mov_b32 s26, 0x18000
	s_mov_b32 s27, 0x1a000
	s_mov_b32 s28, 0x1c000
	s_mov_b32 s29, 0x1e000
	s_mov_b32 s30, 0x20000
	s_mov_b32 s31, 0x22000
	s_mov_b32 s33, 0x24000
	s_mov_b32 s34, 0x26000
	s_mov_b32 s35, 0x28000
	s_mov_b32 s36, 0x2a000
	s_mov_b32 s37, 0x2c000
	s_mov_b32 s39, 0x2e000
	s_mov_b32 s44, 0x30000
	s_mov_b32 s45, 0x32000
	s_mov_b32 s46, 0x34000
	s_mov_b32 s47, 0x36000
	s_mov_b32 s48, 0x38000
	s_mov_b32 s49, 0x3a000
	s_mov_b32 s50, 0x3c000
	s_mov_b32 s51, 0x3e000
	s_mov_b32 s52, 0x40000
	s_mov_b32 s53, 0x50000
	s_mov_b32 s54, 0x60000
	s_mov_b32 s55, 0x70000
	s_mov_b32 s56, 0x80000
	s_mov_b32 s57, 0x90000
	s_mov_b32 s58, 0xa0000
	s_mov_b32 s59, 0xb0000
	s_mov_b32 s60, 0xc0000
	s_mov_b32 s61, 0xd0000
	s_mov_b32 s62, 0xe0000
	s_mov_b32 s63, 0xf0000
	s_mov_b32 s64, 0x100000
	s_mov_b32 s65, 0x110000
	s_mov_b32 s66, 0x120000
	s_mov_b32 s67, 0x130000
	s_mov_b32 s68, 0x140000
	s_mov_b32 s69, 0x150000
	s_mov_b32 s70, 0x160000
	s_mov_b32 s71, 0x170000
	s_mov_b32 s72, 0x180000
	s_mov_b32 s73, 0x190000
	s_mov_b32 s74, 0x1a0000
	s_mov_b32 s75, 0x1b0000
	s_mov_b32 s76, 0x1c0000
	s_mov_b32 s77, 0x1d0000
	s_mov_b32 s78, 0x1e0000
	v_add_u32_e32 v22, 0x400, v28
	v_add_u32_e32 v23, 0x800, v28
	v_add_u32_e32 v24, 0xc00, v28
	v_add_u32_e32 v25, 0x1000, v28
	v_add_u32_e32 v26, 0x1400, v28
	v_add_u32_e32 v27, 0x1800, v28
	v_add_u32_e32 v32, 0x1c00, v28
	s_mov_b32 s79, 0x1f0000
	s_movk_i32 s80, 0xc10
	s_movk_i32 s81, 0xa30
	s_movk_i32 s82, 0x28c0
	s_mov_b32 s83, s2
	s_branch .LBB0_13

.LBB0_12:
	s_add_i32 s83, s83, s43
	s_add_i32 s13, s13, s14
	s_add_i32 s15, s15, s16
	s_add_i32 s17, s17, s18
	s_add_i32 s19, s19, s20
	s_cmp_gt_i32 s83, s100
	s_cbranch_scc1 .LBB0_160

.LBB0_160:
	s_cmp_lg_u32 s101, 0
	s_cbranch_scc1 .Lcv_relay_ret
	s_mov_b64 s[76:77], s[88:89]
	v_and_b32_e32 v20, 63, v0
	s_cmpk_gt_i32 s2, 0x407f
	v_mbcnt_lo_u32_b32 v166, -1, 0
	s_mov_b32 s72, s86
	s_mov_b64 s[78:79], s[90:91]
	s_cbranch_scc1 .LBB0_165
	v_mbcnt_hi_u32_b32 v4, -1, v166
	v_and_b32_e32 v5, 64, v4
	v_add_u32_e32 v5, 64, v5
	v_xor_b32_e32 v6, 1, v4
	v_cmp_lt_i32_e32 vcc, v6, v5
	s_load_dwordx2 s[4:5], s[0:1], 0x48
	v_mov_b32_e32 v3, 0
	v_cndmask_b32_e32 v6, v4, v6, vcc
	v_lshlrev_b32_e32 v19, 2, v6
	v_xor_b32_e32 v6, 2, v4
	v_cmp_lt_i32_e32 vcc, v6, v5
	v_lshlrev_b32_e32 v2, 4, v20
	s_waitcnt lgkmcnt(0)
	v_lshl_add_u64 v[22:23], s[4:5], 0, v[2:3]
	v_cndmask_b32_e32 v6, v4, v6, vcc
	v_lshlrev_b32_e32 v32, 2, v6
	v_xor_b32_e32 v6, 4, v4
	v_cmp_lt_i32_e32 vcc, v6, v5
	s_mov_b64 s[4:5], 0x4200000
	v_lshl_add_u64 v[26:27], s[76:77], 0, v[2:3]
	v_cndmask_b32_e32 v6, v4, v6, vcc
	v_lshlrev_b32_e32 v33, 2, v6
	v_xor_b32_e32 v6, 8, v4
	v_cmp_lt_i32_e32 vcc, v6, v5
	v_lshlrev_b32_e32 v37, 4, v20
	v_mov_b32_e32 v38, 0x358637bd
	v_cndmask_b32_e32 v6, v4, v6, vcc
	v_lshlrev_b32_e32 v34, 2, v6
	v_xor_b32_e32 v6, 16, v4
	v_cmp_lt_i32_e32 vcc, v6, v5
	s_mov_b32 s3, 0xf800000
	v_mov_b32_e32 v39, 0x260
	v_cndmask_b32_e32 v6, v4, v6, vcc
	v_lshlrev_b32_e32 v35, 2, v6
	v_xor_b32_e32 v6, 32, v4
	v_cmp_lt_i32_e32 vcc, v6, v5
	v_mov_b32_e32 v5, v3
	s_nop 0
	v_cndmask_b32_e32 v4, v4, v6, vcc
	v_lshlrev_b32_e32 v36, 2, v4
	v_lshlrev_b32_e32 v4, 3, v20
	v_lshl_add_u64 v[4:5], s[78:79], 0, v[4:5]
	v_lshl_add_u64 v[24:25], v[4:5], 0, s[4:5]
	s_mov_b32 s4, s2
	s_branch .LBB0_163

.Lcv_relay_fwd:
	s_branch .Lcv_loop_entry

.LBB0_2040:
	s_waitcnt vmcnt(0)
	s_barrier
	v_readlane_b32 s100, v254, 43
	v_readlane_b32 s101, v254, 19
	s_cmp_lg_u32 s100, 0
	s_cbranch_scc1 .Lcv2_skip
	s_cmpk_lt_u32 s101, 32
	s_cbranch_scc1 .Lcv2_skip
	v_writelane_b32 v200, s2, 0
	v_writelane_b32 v200, s3, 1
	v_writelane_b32 v200, s4, 2
	v_writelane_b32 v200, s5, 3
	v_writelane_b32 v200, s6, 4
	v_writelane_b32 v200, s7, 5
	v_writelane_b32 v200, s8, 6
	v_writelane_b32 v200, s9, 7
	v_writelane_b32 v200, s10, 8
	v_writelane_b32 v200, s11, 9
	v_writelane_b32 v200, s12, 10
	v_writelane_b32 v200, s13, 11
	v_writelane_b32 v200, s14, 12
	v_writelane_b32 v200, s15, 13
	v_writelane_b32 v200, s16, 14
	v_writelane_b32 v200, s17, 15
	v_writelane_b32 v200, s18, 16
	v_writelane_b32 v200, s19, 17
	v_writelane_b32 v200, s20, 18
	v_writelane_b32 v200, s21, 19
	v_writelane_b32 v200, s22, 20
	v_writelane_b32 v200, s23, 21
	v_writelane_b32 v200, s24, 22
	v_writelane_b32 v200, s25, 23
	v_writelane_b32 v200, s26, 24
	v_writelane_b32 v200, s27, 25
	v_writelane_b32 v200, s28, 26
	v_writelane_b32 v200, s29, 27
	v_writelane_b32 v200, s30, 28
	v_writelane_b32 v200, s31, 29
	v_writelane_b32 v200, s32, 30
	v_writelane_b32 v200, s33, 31
	v_writelane_b32 v200, s34, 32
	v_writelane_b32 v200, s35, 33
	v_writelane_b32 v200, s36, 34
	v_writelane_b32 v200, s37, 35
	v_writelane_b32 v200, s38, 36
	v_writelane_b32 v200, s39, 37
	v_writelane_b32 v200, s40, 38
	v_writelane_b32 v200, s41, 39
	v_writelane_b32 v200, s42, 40
	v_writelane_b32 v200, s43, 41
	v_writelane_b32 v200, s44, 42
	v_writelane_b32 v200, s45, 43
	v_writelane_b32 v200, s46, 44
	v_writelane_b32 v200, s47, 45
	v_writelane_b32 v200, s48, 46
	v_writelane_b32 v200, s49, 47
	v_writelane_b32 v200, s50, 48
	v_writelane_b32 v200, s51, 49
	v_writelane_b32 v200, s52, 50
	v_writelane_b32 v200, s53, 51
	v_writelane_b32 v200, s54, 52
	v_writelane_b32 v200, s55, 53
	v_writelane_b32 v200, s56, 54
	v_writelane_b32 v200, s57, 55
	v_writelane_b32 v200, s58, 56
	v_writelane_b32 v200, s59, 57
	v_writelane_b32 v200, s60, 58
	v_writelane_b32 v200, s61, 59
	v_writelane_b32 v200, s62, 60
	v_writelane_b32 v200, s63, 61
	v_writelane_b32 v200, s64, 62
	v_writelane_b32 v200, s65, 63
	v_writelane_b32 v201, s66, 0
	v_writelane_b32 v201, s67, 1
	v_writelane_b32 v201, s68, 2
	v_writelane_b32 v201, s69, 3
	v_writelane_b32 v201, s70, 4
	v_writelane_b32 v201, s71, 5
	v_writelane_b32 v201, s72, 6
	v_writelane_b32 v201, s73, 7
	v_writelane_b32 v201, s74, 8
	v_writelane_b32 v201, s75, 9
	v_writelane_b32 v201, s76, 10
	v_writelane_b32 v201, s77, 11
	v_writelane_b32 v201, s78, 12
	v_writelane_b32 v201, s79, 13
	v_writelane_b32 v201, s80, 14
	v_writelane_b32 v201, s81, 15
	v_writelane_b32 v201, s82, 16
	v_writelane_b32 v201, s83, 17
	v_writelane_b32 v201, s84, 18
	v_writelane_b32 v201, s85, 19
	v_writelane_b32 v201, s86, 20
	v_writelane_b32 v201, s87, 21
	v_writelane_b32 v201, s88, 22
	v_writelane_b32 v201, s89, 23
	v_writelane_b32 v201, s90, 24
	v_writelane_b32 v201, s91, 25
	v_writelane_b32 v201, s92, 26
	v_writelane_b32 v201, s93, 27
	v_writelane_b32 v201, s94, 28
	v_writelane_b32 v201, s95, 29
	v_writelane_b32 v201, s96, 30
	v_writelane_b32 v201, s97, 31
	v_writelane_b32 v201, s98, 32
	v_writelane_b32 v201, s99, 33
	s_load_dwordx4 s[88:91], s[0:1], 0xb8
	v_mbcnt_lo_u32_b32 v0, -1, 0
	v_mbcnt_hi_u32_b32 v0, -1, v0
	v_readlane_b32 s87, v255, 4
	s_waitcnt lgkmcnt(0)
	v_and_b32_e32 v21, 31, v0
	v_bfe_u32 v31, v0, 5, 1
	v_lshlrev_b32_e32 v2, 2, v21
	v_mul_u32_u24_e32 v3, 0x84, v31
	v_bfe_u32 v29, v0, 3, 3
	s_lshl_b32 s2, s87, 14
	s_add_i32 s3, s2, 0
	v_add3_u32 v28, s3, v2, v3
	v_lshlrev_b32_e32 v2, 3, v0
	v_and_b32_e32 v2, 56, v2
	v_mul_u32_u24_e32 v4, 0x84, v2
	v_lshlrev_b32_e32 v5, 2, v29
	s_mov_b32 s7, 0
	v_mov_b32_e32 v3, 0
	v_add3_u32 v30, s3, v4, v5
	v_lshlrev_b32_e32 v18, 1, v2
	s_sub_i32 s2, s101, 32
	s_lshl_b32 s2, s2, 3
	s_add_i32 s2, s2, s87
	s_addk_i32 s2, 0x2000
	s_movk_i32 s43, 0x700
	s_movk_i32 s100, 0x3fff
	s_mov_b32 s101, 2
	s_branch .Lcv_relay_fwd
.Lcv2_ret:
	v_readlane_b32 s2, v200, 0
	v_readlane_b32 s3, v200, 1
	v_readlane_b32 s4, v200, 2
	v_readlane_b32 s5, v200, 3
	v_readlane_b32 s6, v200, 4
	v_readlane_b32 s7, v200, 5
	v_readlane_b32 s8, v200, 6
	v_readlane_b32 s9, v200, 7
	v_readlane_b32 s10, v200, 8
	v_readlane_b32 s11, v200, 9
	v_readlane_b32 s12, v200, 10
	v_readlane_b32 s13, v200, 11
	v_readlane_b32 s14, v200, 12
	v_readlane_b32 s15, v200, 13
	v_readlane_b32 s16, v200, 14
	v_readlane_b32 s17, v200, 15
	v_readlane_b32 s18, v200, 16
	v_readlane_b32 s19, v200, 17
	v_readlane_b32 s20, v200, 18
	v_readlane_b32 s21, v200, 19
	v_readlane_b32 s22, v200, 20
	v_readlane_b32 s23, v200, 21
	v_readlane_b32 s24, v200, 22
	v_readlane_b32 s25, v200, 23
	v_readlane_b32 s26, v200, 24
	v_readlane_b32 s27, v200, 25
	v_readlane_b32 s28, v200, 26
	v_readlane_b32 s29, v200, 27
	v_readlane_b32 s30, v200, 28
	v_readlane_b32 s31, v200, 29
	v_readlane_b32 s32, v200, 30
	v_readlane_b32 s33, v200, 31
	v_readlane_b32 s34, v200, 32
	v_readlane_b32 s35, v200, 33
	v_readlane_b32 s36, v200, 34
	v_readlane_b32 s37, v200, 35
	v_readlane_b32 s38, v200, 36
	v_readlane_b32 s39, v200, 37
	v_readlane_b32 s40, v200, 38
	v_readlane_b32 s41, v200, 39
	v_readlane_b32 s42, v200, 40
	v_readlane_b32 s43, v200, 41
	v_readlane_b32 s44, v200, 42
	v_readlane_b32 s45, v200, 43
	v_readlane_b32 s46, v200, 44
	v_readlane_b32 s47, v200, 45
	v_readlane_b32 s48, v200, 46
	v_readlane_b32 s49, v200, 47
	v_readlane_b32 s50, v200, 48
	v_readlane_b32 s51, v200, 49
	v_readlane_b32 s52, v200, 50
	v_readlane_b32 s53, v200, 51
	v_readlane_b32 s54, v200, 52
	v_readlane_b32 s55, v200, 53
	v_readlane_b32 s56, v200, 54
	v_readlane_b32 s57, v200, 55
	v_readlane_b32 s58, v200, 56
	v_readlane_b32 s59, v200, 57
	v_readlane_b32 s60, v200, 58
	v_readlane_b32 s61, v200, 59
	v_readlane_b32 s62, v200, 60
	v_readlane_b32 s63, v200, 61
	v_readlane_b32 s64, v200, 62
	v_readlane_b32 s65, v200, 63
	v_readlane_b32 s66, v201, 0
	v_readlane_b32 s67, v201, 1
	v_readlane_b32 s68, v201, 2
	v_readlane_b32 s69, v201, 3
	v_readlane_b32 s70, v201, 4
	v_readlane_b32 s71, v201, 5
	v_readlane_b32 s72, v201, 6
	v_readlane_b32 s73, v201, 7
	v_readlane_b32 s74, v201, 8
	v_readlane_b32 s75, v201, 9
	v_readlane_b32 s76, v201, 10
	v_readlane_b32 s77, v201, 11
	v_readlane_b32 s78, v201, 12
	v_readlane_b32 s79, v201, 13
	v_readlane_b32 s80, v201, 14
	v_readlane_b32 s81, v201, 15
	v_readlane_b32 s82, v201, 16
	v_readlane_b32 s83, v201, 17
	v_readlane_b32 s84, v201, 18
	v_readlane_b32 s85, v201, 19
	v_readlane_b32 s86, v201, 20
	v_readlane_b32 s87, v201, 21
	v_readlane_b32 s88, v201, 22
	v_readlane_b32 s89, v201, 23
	v_readlane_b32 s90, v201, 24
	v_readlane_b32 s91, v201, 25
	v_readlane_b32 s92, v201, 26
	v_readlane_b32 s93, v201, 27
	v_readlane_b32 s94, v201, 28
	v_readlane_b32 s95, v201, 29
	v_readlane_b32 s96, v201, 30
	v_readlane_b32 s97, v201, 31
	v_readlane_b32 s98, v201, 32
	v_readlane_b32 s99, v201, 33
.Lcv2_skip:
	s_waitcnt vmcnt(0)
	v_readlane_b32 s72, v255, 46
	v_readlane_b32 s73, v255, 47
	s_and_b64 vcc, exec, s[72:73]
	s_barrier
	s_cbranch_vccnz .LBB0_2086
	s_mov_b32 s2, -1
	s_nop 0
	v_mbcnt_lo_u32_b32 v0, s2, 0
	v_mbcnt_hi_u32_b32 v0, s2, v0
	v_cmp_eq_u32_e32 vcc, 0, v0
	s_and_saveexec_b64 s[60:61], vcc
	s_cbranch_execz .LBB0_2085
	v_readlane_b32 s62, v254, 4
	v_readlane_b32 s3, v255, 39
	s_mov_b32 s2, s83
	v_readlane_b32 s63, v254, 5
	v_mov_b32_e32 v0, s3
	s_waitcnt vmcnt(0) expcnt(0) lgkmcnt(0)
	ds_read_b32 v2, v0
	v_readlane_b32 s3, v255, 40
	s_waitcnt lgkmcnt(0)
	v_cmp_ne_u32_e32 vcc, 0, v2
	v_mov_b32_e32 v0, s3
	ds_read_b32 v0, v0
	s_cbranch_vccnz .LBB0_2056
	v_readlane_b32 s6, v254, 0
	v_readlane_b32 s7, v254, 1
	s_load_dwordx2 s[4:5], s[6:7], 0x4
	s_add_u32 s6, s62, 0x1000
	s_addc_u32 s7, s63, 0
	s_add_u32 s8, s62, 0x1100
	s_addc_u32 s9, s63, 0
	s_add_u32 s10, s62, 0x1200
	s_addc_u32 s11, s63, 0
	s_waitcnt lgkmcnt(0)
	s_mul_i32 s3, s4, s38
	s_add_u32 s12, s62, 0x1300
	s_mul_i32 s3, s3, s5
	s_addc_u32 s13, s63, 0
	s_mov_b32 s4, 1
	s_mov_b64 s[14:15], 0
	s_branch .LBB0_2046
